# v73 + GEMM unit start: accumulators cleared with 63 v_mov_b64 + 1 v_mov_b32 instead of 127 v_mov_b32 (P1 both instances, P5)
# speedup vs baseline: 1.0019x; 1.0019x over previous
.LBB0_143:
	s_add_i32 s41, s41, 1
	s_mov_b64 s[24:25], s[0:1]
	s_mul_i32 s0, s41, 24
	s_add_i32 s0, s0, s30
	s_cmp_lt_i32 s0, 32
	s_cselect_b64 s[20:21], -1, 0
	s_lshr_b32 s0, s0, 2
	s_mov_b64 s[22:23], s[2:3]
	s_mov_b32 s2, s36
	s_mov_b32 s49, s36
	s_add_i32 s36, s0, 0x41
	s_and_b64 s[0:1], s[20:21], exec
	s_cselect_b32 s2, s36, s2
	s_cselect_b32 s0, s33, s33
	s_ashr_i32 s3, s2, 31
	s_lshl_b64 s[2:3], s[2:3], 19
	s_add_u32 s2, s90, s2
	s_addc_u32 s3, s91, s3
	s_and_b64 s[28:29], s[20:21], exec
	s_cselect_b32 s50, s3, s23
	s_cselect_b32 s51, s2, s22
	s_ashr_i32 s1, s0, 31
	s_lshl_b64 s[0:1], s[0:1], 19
	s_add_u32 s0, s92, s0
	s_addc_u32 s1, s93, s1
	s_and_b64 s[28:29], s[20:21], exec
	s_cselect_b32 s56, s1, s25
	s_cselect_b32 s57, s0, s24
	s_add_u32 s22, s22, 0x40080
	s_addc_u32 s23, s23, 0
	s_add_u32 s58, s24, 0x100
	v_mov_b32_e32 v2, 0
	s_addc_u32 s59, s25, 0
	s_mov_b32 s60, -2
	v_mov_b32_e32 v3, 0
	v_mov_b64_e32 v[4:5], 0
	v_mov_b64_e32 v[6:7], 0
	v_mov_b64_e32 v[8:9], 0
	v_mov_b64_e32 v[10:11], 0
	v_mov_b64_e32 v[12:13], 0
	v_mov_b64_e32 v[14:15], 0
	v_mov_b64_e32 v[16:17], 0
	v_mov_b64_e32 v[18:19], 0
	v_mov_b64_e32 v[20:21], 0
	v_mov_b64_e32 v[22:23], 0
	v_mov_b64_e32 v[24:25], 0
	v_mov_b64_e32 v[26:27], 0
	v_mov_b64_e32 v[28:29], 0
	v_mov_b64_e32 v[30:31], 0
	v_mov_b64_e32 v[32:33], 0
	v_mov_b64_e32 v[34:35], 0
	v_mov_b64_e32 v[36:37], 0
	v_mov_b64_e32 v[38:39], 0
	v_mov_b64_e32 v[40:41], 0
	v_mov_b64_e32 v[42:43], 0
	v_mov_b64_e32 v[44:45], 0
	v_mov_b64_e32 v[46:47], 0
	v_mov_b64_e32 v[48:49], 0
	v_mov_b64_e32 v[50:51], 0
	v_mov_b64_e32 v[52:53], 0
	v_mov_b64_e32 v[54:55], 0
	v_mov_b64_e32 v[56:57], 0
	v_mov_b64_e32 v[58:59], 0
	v_mov_b64_e32 v[60:61], 0
	v_mov_b64_e32 v[62:63], 0
	v_mov_b64_e32 v[64:65], 0
	v_mov_b64_e32 v[66:67], 0
	v_mov_b64_e32 v[68:69], 0
	v_mov_b64_e32 v[70:71], 0
	v_mov_b64_e32 v[72:73], 0
	v_mov_b64_e32 v[74:75], 0
	v_mov_b64_e32 v[76:77], 0
	v_mov_b64_e32 v[78:79], 0
	v_mov_b64_e32 v[80:81], 0
	v_mov_b64_e32 v[82:83], 0
	v_mov_b64_e32 v[84:85], 0
	v_mov_b64_e32 v[86:87], 0
	v_mov_b64_e32 v[88:89], 0
	v_mov_b64_e32 v[90:91], 0
	v_mov_b64_e32 v[92:93], 0
	v_mov_b64_e32 v[94:95], 0
	v_mov_b64_e32 v[96:97], 0
	v_mov_b64_e32 v[98:99], 0
	v_mov_b64_e32 v[100:101], 0
	v_mov_b64_e32 v[102:103], 0
	v_mov_b64_e32 v[104:105], 0
	v_mov_b64_e32 v[106:107], 0
	v_mov_b64_e32 v[108:109], 0
	v_mov_b64_e32 v[110:111], 0
	v_mov_b64_e32 v[112:113], 0
	v_mov_b64_e32 v[114:115], 0
	v_mov_b64_e32 v[116:117], 0
	v_mov_b64_e32 v[118:119], 0
	v_mov_b64_e32 v[120:121], 0
	v_mov_b64_e32 v[122:123], 0
	v_mov_b64_e32 v[124:125], 0
	v_mov_b64_e32 v[126:127], 0
	v_mov_b64_e32 v[128:129], 0

.LBB0_259:
	s_mov_b32 s26, s7
	s_ashr_i32 s27, s7, 31
	s_mov_b32 s64, s6
	s_lshl_b64 s[6:7], s[26:27], 19
	s_add_u32 s68, s90, s6
	s_addc_u32 s69, s91, s7
	s_and_b64 s[6:7], s[66:67], exec
	s_cselect_b32 s8, s69, s1
	s_cselect_b32 s9, s68, s0
	s_ashr_i32 s65, s64, 31
	s_lshl_b64 s[6:7], s[64:65], 19
	s_add_u32 s88, s92, s6
	s_addc_u32 s89, s93, s7
	s_and_b64 s[6:7], s[66:67], exec
	s_cselect_b32 s10, s89, s5
	s_cselect_b32 s11, s88, s4
	s_add_u32 s0, s0, 0x40080
	s_addc_u32 s1, s1, 0
	s_add_u32 s13, s4, 0x100
	v_mov_b32_e32 v2, 0
	s_addc_u32 s22, s5, 0
	s_mov_b32 s23, -2
	v_mov_b32_e32 v3, 0
	v_mov_b64_e32 v[4:5], 0
	v_mov_b64_e32 v[6:7], 0
	v_mov_b64_e32 v[8:9], 0
	v_mov_b64_e32 v[10:11], 0
	v_mov_b64_e32 v[12:13], 0
	v_mov_b64_e32 v[14:15], 0
	v_mov_b64_e32 v[16:17], 0
	v_mov_b64_e32 v[18:19], 0
	v_mov_b64_e32 v[20:21], 0
	v_mov_b64_e32 v[22:23], 0
	v_mov_b64_e32 v[24:25], 0
	v_mov_b64_e32 v[26:27], 0
	v_mov_b64_e32 v[28:29], 0
	v_mov_b64_e32 v[30:31], 0
	v_mov_b64_e32 v[32:33], 0
	v_mov_b64_e32 v[34:35], 0
	v_mov_b64_e32 v[36:37], 0
	v_mov_b64_e32 v[38:39], 0
	v_mov_b64_e32 v[40:41], 0
	v_mov_b64_e32 v[42:43], 0
	v_mov_b64_e32 v[44:45], 0
	v_mov_b64_e32 v[46:47], 0
	v_mov_b64_e32 v[48:49], 0
	v_mov_b64_e32 v[50:51], 0
	v_mov_b64_e32 v[52:53], 0
	v_mov_b64_e32 v[54:55], 0
	v_mov_b64_e32 v[56:57], 0
	v_mov_b64_e32 v[58:59], 0
	v_mov_b64_e32 v[60:61], 0
	v_mov_b64_e32 v[62:63], 0
	v_mov_b64_e32 v[64:65], 0
	v_mov_b64_e32 v[66:67], 0
	v_mov_b64_e32 v[68:69], 0
	v_mov_b64_e32 v[70:71], 0
	v_mov_b64_e32 v[72:73], 0
	v_mov_b64_e32 v[74:75], 0
	v_mov_b64_e32 v[76:77], 0
	v_mov_b64_e32 v[78:79], 0
	v_mov_b64_e32 v[80:81], 0
	v_mov_b64_e32 v[82:83], 0
	v_mov_b64_e32 v[84:85], 0
	v_mov_b64_e32 v[86:87], 0
	v_mov_b64_e32 v[88:89], 0
	v_mov_b64_e32 v[90:91], 0
	v_mov_b64_e32 v[92:93], 0
	v_mov_b64_e32 v[94:95], 0
	v_mov_b64_e32 v[96:97], 0
	v_mov_b64_e32 v[98:99], 0
	v_mov_b64_e32 v[100:101], 0
	v_mov_b64_e32 v[102:103], 0
	v_mov_b64_e32 v[104:105], 0
	v_mov_b64_e32 v[106:107], 0
	v_mov_b64_e32 v[108:109], 0
	v_mov_b64_e32 v[110:111], 0
	v_mov_b64_e32 v[112:113], 0
	v_mov_b64_e32 v[114:115], 0
	v_mov_b64_e32 v[116:117], 0
	v_mov_b64_e32 v[118:119], 0
	v_mov_b64_e32 v[120:121], 0
	v_mov_b64_e32 v[122:123], 0
	v_mov_b64_e32 v[124:125], 0
	v_mov_b64_e32 v[126:127], 0
	v_mov_b64_e32 v[128:129], 0

.LBB0_1174:
	v_add_u32_e32 v147, s43, v1
	ds_read_b128 v[148:151], v147
	ds_read_b128 v[152:155], v147 offset:1024
	ds_read_b128 v[156:159], v147 offset:2048
	ds_read_b128 v[160:163], v147 offset:3072
	v_add_u32_e32 v147, s44, v1
	s_add_u32 s24, s10, s22
	ds_read_b128 v[164:167], v147
	ds_read_b128 v[168:171], v147 offset:1024
	ds_read_b128 v[172:175], v147 offset:2048
	ds_read_b128 v[176:179], v147 offset:3072
	s_addc_u32 s25, s11, s23
	s_add_u32 s24, s24, 0x100
	s_addc_u32 s25, s25, 0
	s_add_u32 s51, s46, s22
	s_addc_u32 s52, s47, s23
	s_cmpk_eq_i32 s22, 0xf00
	s_cselect_b32 s29, s17, s25
	s_cselect_b32 s28, s48, s24
	s_cselect_b32 s25, s15, s52
	s_cselect_b32 s24, s49, s51
	v_lshl_add_u64 v[212:213], v[142:143], 0, s[22:23]
	s_add_i32 m0, s9, 0xc000
	ds_read_b128 v[180:183], v146
	ds_read_b128 v[184:187], v146 offset:1024
	ds_read_b128 v[188:191], v146 offset:2048
	ds_read_b128 v[192:195], v146 offset:3072
	ds_read_b128 v[196:199], v146 offset:4096
	ds_read_b128 v[200:203], v146 offset:5120
	ds_read_b128 v[204:207], v146 offset:6144
	ds_read_b128 v[208:211], v146 offset:7168
	global_load_lds_dwordx4 v[212:213], off
	v_lshl_add_u64 v[212:213], v[144:145], 0, s[22:23]
	s_add_i32 m0, s9, 0xe000
	s_nop 0
	global_load_lds_dwordx4 v[212:213], off
	s_waitcnt vmcnt(8)
	s_waitcnt lgkmcnt(0)
	s_barrier
	s_setprio 1
	s_waitcnt lgkmcnt(0)
	v_mfma_f32_16x16x32_bf16 v[86:89], v[148:151], v[180:183], v[86:89]
	v_mfma_f32_16x16x32_bf16 v[82:85], v[156:159], v[180:183], v[82:85]
	v_mfma_f32_16x16x32_bf16 v[126:129], v[148:151], v[188:191], v[126:129]
	v_mfma_f32_16x16x32_bf16 v[110:113], v[156:159], v[188:191], v[110:113]
	v_mfma_f32_16x16x32_bf16 v[122:125], v[148:151], v[196:199], v[122:125]
	v_mfma_f32_16x16x32_bf16 v[118:121], v[156:159], v[196:199], v[118:121]
	v_mfma_f32_16x16x32_bf16 v[98:101], v[148:151], v[204:207], v[98:101]
	v_mfma_f32_16x16x32_bf16 v[94:97], v[156:159], v[204:207], v[94:97]
	v_mfma_f32_16x16x32_bf16 v[86:89], v[152:155], v[184:187], v[86:89]
	v_mfma_f32_16x16x32_bf16 v[82:85], v[160:163], v[184:187], v[82:85]
	v_mfma_f32_16x16x32_bf16 v[126:129], v[152:155], v[192:195], v[126:129]
	v_mfma_f32_16x16x32_bf16 v[110:113], v[160:163], v[192:195], v[110:113]
	v_mfma_f32_16x16x32_bf16 v[122:125], v[152:155], v[200:203], v[122:125]
	v_mfma_f32_16x16x32_bf16 v[118:121], v[160:163], v[200:203], v[118:121]
	v_mfma_f32_16x16x32_bf16 v[98:101], v[152:155], v[208:211], v[98:101]
	v_mfma_f32_16x16x32_bf16 v[94:97], v[160:163], v[208:211], v[94:97]
	s_setprio 0
	s_setprio 1
	v_mfma_f32_16x16x32_bf16 v[78:81], v[164:167], v[180:183], v[78:81]
	v_mfma_f32_16x16x32_bf16 v[74:77], v[172:175], v[180:183], v[74:77]
	v_mfma_f32_16x16x32_bf16 v[102:105], v[164:167], v[188:191], v[102:105]
	v_mfma_f32_16x16x32_bf16 v[90:93], v[172:175], v[188:191], v[90:93]
	v_mfma_f32_16x16x32_bf16 v[114:117], v[164:167], v[196:199], v[114:117]
	v_mfma_f32_16x16x32_bf16 v[106:109], v[172:175], v[196:199], v[106:109]
	v_mfma_f32_16x16x32_bf16 v[70:73], v[164:167], v[204:207], v[70:73]
	v_mfma_f32_16x16x32_bf16 v[66:69], v[172:175], v[204:207], v[66:69]
	v_mfma_f32_16x16x32_bf16 v[78:81], v[168:171], v[184:187], v[78:81]
	v_mfma_f32_16x16x32_bf16 v[74:77], v[176:179], v[184:187], v[74:77]
	v_mfma_f32_16x16x32_bf16 v[102:105], v[168:171], v[192:195], v[102:105]
	v_mfma_f32_16x16x32_bf16 v[90:93], v[176:179], v[192:195], v[90:93]
	v_mfma_f32_16x16x32_bf16 v[114:117], v[168:171], v[200:203], v[114:117]
	v_mfma_f32_16x16x32_bf16 v[106:109], v[176:179], v[200:203], v[106:109]
	v_mfma_f32_16x16x32_bf16 v[70:73], v[168:171], v[208:211], v[70:73]
	v_mfma_f32_16x16x32_bf16 v[66:69], v[176:179], v[208:211], v[66:69]
	s_setprio 0
	s_barrier
	s_add_i32 s51, s43, s36
	v_lshl_add_u64 v[212:213], s[24:25], 0, v[130:131]
	s_mov_b32 m0, s51
	ds_read_b128 v[180:183], v146 offset:16384
	ds_read_b128 v[184:187], v146 offset:17408
	ds_read_b128 v[188:191], v146 offset:18432
	ds_read_b128 v[192:195], v146 offset:19456
	ds_read_b128 v[196:199], v146 offset:20480
	ds_read_b128 v[200:203], v146 offset:21504
	ds_read_b128 v[204:207], v146 offset:22528
	ds_read_b128 v[208:211], v146 offset:23552
	global_load_lds_dwordx4 v[212:213], off
	s_add_i32 m0, s51, 0x2000
	s_add_u32 s52, s24, 0x80000
	v_lshl_add_u64 v[214:215], s[24:25], 0, v[132:133]
	s_addc_u32 s53, s25, 0
	s_add_i32 s51, s44, s36
	global_load_lds_dwordx4 v[214:215], off
	v_lshl_add_u64 v[216:217], s[52:53], 0, v[130:131]
	s_mov_b32 m0, s51
	v_lshl_add_u64 v[218:219], s[28:29], 0, v[132:133]
	global_load_lds_dwordx4 v[216:217], off
	v_lshl_add_u64 v[216:217], s[52:53], 0, v[132:133]
	s_add_i32 m0, s51, 0x2000
	s_nop 0
	global_load_lds_dwordx4 v[216:217], off
	v_lshl_add_u64 v[216:217], s[28:29], 0, v[130:131]
	s_mov_b32 m0, s9
	s_nop 0
	global_load_lds_dwordx4 v[216:217], off
	s_mov_b32 m0, s37
	s_nop 0
	global_load_lds_dwordx4 v[218:219], off
	s_waitcnt vmcnt(8)
	s_waitcnt lgkmcnt(0)
	s_barrier
	s_setprio 1
	s_waitcnt lgkmcnt(0)
	v_mfma_f32_16x16x32_bf16 v[62:65], v[148:151], v[180:183], v[62:65]
	v_mfma_f32_16x16x32_bf16 v[58:61], v[156:159], v[180:183], v[58:61]
	v_mfma_f32_16x16x32_bf16 v[46:49], v[148:151], v[188:191], v[46:49]
	v_mfma_f32_16x16x32_bf16 v[42:45], v[156:159], v[188:191], v[42:45]
	v_mfma_f32_16x16x32_bf16 v[30:33], v[148:151], v[196:199], v[30:33]
	v_mfma_f32_16x16x32_bf16 v[26:29], v[156:159], v[196:199], v[26:29]
	v_mfma_f32_16x16x32_bf16 v[14:17], v[148:151], v[204:207], v[14:17]
	v_mfma_f32_16x16x32_bf16 v[10:13], v[156:159], v[204:207], v[10:13]
	v_mfma_f32_16x16x32_bf16 v[62:65], v[152:155], v[184:187], v[62:65]
	v_mfma_f32_16x16x32_bf16 v[58:61], v[160:163], v[184:187], v[58:61]
	v_mfma_f32_16x16x32_bf16 v[46:49], v[152:155], v[192:195], v[46:49]
	v_mfma_f32_16x16x32_bf16 v[42:45], v[160:163], v[192:195], v[42:45]
	v_mfma_f32_16x16x32_bf16 v[30:33], v[152:155], v[200:203], v[30:33]
	v_mfma_f32_16x16x32_bf16 v[26:29], v[160:163], v[200:203], v[26:29]
	v_mfma_f32_16x16x32_bf16 v[14:17], v[152:155], v[208:211], v[14:17]
	v_mfma_f32_16x16x32_bf16 v[10:13], v[160:163], v[208:211], v[10:13]
	s_setprio 0
	s_setprio 1
	v_mfma_f32_16x16x32_bf16 v[54:57], v[164:167], v[180:183], v[54:57]
	v_mfma_f32_16x16x32_bf16 v[50:53], v[172:175], v[180:183], v[50:53]
	v_mfma_f32_16x16x32_bf16 v[38:41], v[164:167], v[188:191], v[38:41]
	v_mfma_f32_16x16x32_bf16 v[34:37], v[172:175], v[188:191], v[34:37]
	v_mfma_f32_16x16x32_bf16 v[22:25], v[164:167], v[196:199], v[22:25]
	v_mfma_f32_16x16x32_bf16 v[18:21], v[172:175], v[196:199], v[18:21]
	v_mfma_f32_16x16x32_bf16 v[6:9], v[164:167], v[204:207], v[6:9]
	v_mfma_f32_16x16x32_bf16 v[2:5], v[172:175], v[204:207], v[2:5]
	v_mfma_f32_16x16x32_bf16 v[54:57], v[168:171], v[184:187], v[54:57]
	v_mfma_f32_16x16x32_bf16 v[50:53], v[176:179], v[184:187], v[50:53]
	v_mfma_f32_16x16x32_bf16 v[38:41], v[168:171], v[192:195], v[38:41]
	v_mfma_f32_16x16x32_bf16 v[34:37], v[176:179], v[192:195], v[34:37]
	v_mfma_f32_16x16x32_bf16 v[22:25], v[168:171], v[200:203], v[22:25]
	v_mfma_f32_16x16x32_bf16 v[18:21], v[176:179], v[200:203], v[18:21]
	v_mfma_f32_16x16x32_bf16 v[6:9], v[168:171], v[208:211], v[6:9]
	v_mfma_f32_16x16x32_bf16 v[2:5], v[176:179], v[208:211], v[2:5]
	s_setprio 0
	s_barrier
	s_add_i32 s51, 0, 0x18000
	v_add_u32_e32 v147, s51, v1
	s_add_i32 s52, 0, 0x1c000
	ds_read_b128 v[148:151], v147
	ds_read_b128 v[152:155], v147 offset:1024
	ds_read_b128 v[156:159], v147 offset:2048
	ds_read_b128 v[160:163], v147 offset:3072
	v_add_u32_e32 v147, s52, v1
	ds_read_b128 v[164:167], v147
	ds_read_b128 v[168:171], v147 offset:1024
	ds_read_b128 v[172:175], v147 offset:2048
	ds_read_b128 v[176:179], v147 offset:3072
	s_add_u32 s28, s28, 0x80000
	s_addc_u32 s29, s29, 0
	s_mov_b32 m0, s38
	v_lshl_add_u64 v[220:221], s[28:29], 0, v[130:131]
	ds_read_b128 v[180:183], v146 offset:32768
	ds_read_b128 v[184:187], v146 offset:33792
	ds_read_b128 v[188:191], v146 offset:34816
	ds_read_b128 v[192:195], v146 offset:35840
	ds_read_b128 v[196:199], v146 offset:36864
	ds_read_b128 v[200:203], v146 offset:37888
	ds_read_b128 v[204:207], v146 offset:38912
	ds_read_b128 v[208:211], v146 offset:39936
	global_load_lds_dwordx4 v[220:221], off
	v_lshl_add_u64 v[220:221], s[28:29], 0, v[132:133]
	s_mov_b32 m0, s39
	s_nop 0
	global_load_lds_dwordx4 v[220:221], off
	s_waitcnt vmcnt(8)
	s_waitcnt lgkmcnt(0)
	s_barrier
	s_setprio 1
	s_waitcnt lgkmcnt(0)
	v_mfma_f32_16x16x32_bf16 v[86:89], v[148:151], v[180:183], v[86:89]
	v_mfma_f32_16x16x32_bf16 v[82:85], v[156:159], v[180:183], v[82:85]
	v_mfma_f32_16x16x32_bf16 v[126:129], v[148:151], v[188:191], v[126:129]
	v_mfma_f32_16x16x32_bf16 v[110:113], v[156:159], v[188:191], v[110:113]
	v_mfma_f32_16x16x32_bf16 v[122:125], v[148:151], v[196:199], v[122:125]
	v_mfma_f32_16x16x32_bf16 v[118:121], v[156:159], v[196:199], v[118:121]
	v_mfma_f32_16x16x32_bf16 v[98:101], v[148:151], v[204:207], v[98:101]
	v_mfma_f32_16x16x32_bf16 v[94:97], v[156:159], v[204:207], v[94:97]
	v_mfma_f32_16x16x32_bf16 v[86:89], v[152:155], v[184:187], v[86:89]
	v_mfma_f32_16x16x32_bf16 v[82:85], v[160:163], v[184:187], v[82:85]
	v_mfma_f32_16x16x32_bf16 v[126:129], v[152:155], v[192:195], v[126:129]
	v_mfma_f32_16x16x32_bf16 v[110:113], v[160:163], v[192:195], v[110:113]
	v_mfma_f32_16x16x32_bf16 v[122:125], v[152:155], v[200:203], v[122:125]
	v_mfma_f32_16x16x32_bf16 v[118:121], v[160:163], v[200:203], v[118:121]
	v_mfma_f32_16x16x32_bf16 v[98:101], v[152:155], v[208:211], v[98:101]
	v_mfma_f32_16x16x32_bf16 v[94:97], v[160:163], v[208:211], v[94:97]
	s_setprio 0
	s_setprio 1
	v_mfma_f32_16x16x32_bf16 v[78:81], v[164:167], v[180:183], v[78:81]
	v_mfma_f32_16x16x32_bf16 v[74:77], v[172:175], v[180:183], v[74:77]
	v_mfma_f32_16x16x32_bf16 v[102:105], v[164:167], v[188:191], v[102:105]
	v_mfma_f32_16x16x32_bf16 v[90:93], v[172:175], v[188:191], v[90:93]
	v_mfma_f32_16x16x32_bf16 v[114:117], v[164:167], v[196:199], v[114:117]
	v_mfma_f32_16x16x32_bf16 v[106:109], v[172:175], v[196:199], v[106:109]
	v_mfma_f32_16x16x32_bf16 v[70:73], v[164:167], v[204:207], v[70:73]
	v_mfma_f32_16x16x32_bf16 v[66:69], v[172:175], v[204:207], v[66:69]
	v_mfma_f32_16x16x32_bf16 v[78:81], v[168:171], v[184:187], v[78:81]
	v_mfma_f32_16x16x32_bf16 v[74:77], v[176:179], v[184:187], v[74:77]
	v_mfma_f32_16x16x32_bf16 v[102:105], v[168:171], v[192:195], v[102:105]
	v_mfma_f32_16x16x32_bf16 v[90:93], v[176:179], v[192:195], v[90:93]
	v_mfma_f32_16x16x32_bf16 v[114:117], v[168:171], v[200:203], v[114:117]
	v_mfma_f32_16x16x32_bf16 v[106:109], v[176:179], v[200:203], v[106:109]
	v_mfma_f32_16x16x32_bf16 v[70:73], v[168:171], v[208:211], v[70:73]
	v_mfma_f32_16x16x32_bf16 v[66:69], v[176:179], v[208:211], v[66:69]
	s_setprio 0
	s_barrier
	s_add_i32 s28, s51, s36
	v_lshl_add_u64 v[212:213], v[212:213], 0, s[12:13]
	s_mov_b32 m0, s28
	ds_read_b128 v[180:183], v146 offset:49152
	ds_read_b128 v[184:187], v146 offset:50176
	ds_read_b128 v[188:191], v146 offset:51200
	ds_read_b128 v[192:195], v146 offset:52224
	ds_read_b128 v[196:199], v146 offset:53248
	ds_read_b128 v[200:203], v146 offset:54272
	ds_read_b128 v[204:207], v146 offset:55296
	ds_read_b128 v[208:211], v146 offset:56320
	global_load_lds_dwordx4 v[212:213], off
	s_add_i32 m0, s28, 0x2000
	s_add_u32 s24, s24, 0x80080
	v_lshl_add_u64 v[212:213], v[214:215], 0, s[12:13]
	s_addc_u32 s25, s25, 0
	s_add_i32 s28, s52, s36
	global_load_lds_dwordx4 v[212:213], off
	v_lshl_add_u64 v[212:213], s[24:25], 0, v[130:131]
	s_mov_b32 m0, s28
	s_nop 0
	global_load_lds_dwordx4 v[212:213], off
	v_lshl_add_u64 v[212:213], s[24:25], 0, v[132:133]
	s_add_i32 m0, s28, 0x2000
	s_nop 0
	global_load_lds_dwordx4 v[212:213], off
	v_lshl_add_u64 v[212:213], v[216:217], 0, s[12:13]
	s_mov_b32 m0, s41
	s_nop 0
	global_load_lds_dwordx4 v[212:213], off
	v_lshl_add_u64 v[212:213], v[218:219], 0, s[12:13]
	s_mov_b32 m0, s42
	s_nop 0
	global_load_lds_dwordx4 v[212:213], off
	s_waitcnt vmcnt(8)
	s_waitcnt lgkmcnt(0)
	s_barrier
	s_setprio 1
	s_waitcnt lgkmcnt(0)
	v_mfma_f32_16x16x32_bf16 v[62:65], v[148:151], v[180:183], v[62:65]
	v_mfma_f32_16x16x32_bf16 v[58:61], v[156:159], v[180:183], v[58:61]
	v_mfma_f32_16x16x32_bf16 v[46:49], v[148:151], v[188:191], v[46:49]
	v_mfma_f32_16x16x32_bf16 v[42:45], v[156:159], v[188:191], v[42:45]
	v_mfma_f32_16x16x32_bf16 v[30:33], v[148:151], v[196:199], v[30:33]
	v_mfma_f32_16x16x32_bf16 v[26:29], v[156:159], v[196:199], v[26:29]
	v_mfma_f32_16x16x32_bf16 v[14:17], v[148:151], v[204:207], v[14:17]
	v_mfma_f32_16x16x32_bf16 v[10:13], v[156:159], v[204:207], v[10:13]
	v_mfma_f32_16x16x32_bf16 v[62:65], v[152:155], v[184:187], v[62:65]
	v_mfma_f32_16x16x32_bf16 v[58:61], v[160:163], v[184:187], v[58:61]
	v_mfma_f32_16x16x32_bf16 v[46:49], v[152:155], v[192:195], v[46:49]
	v_mfma_f32_16x16x32_bf16 v[42:45], v[160:163], v[192:195], v[42:45]
	v_mfma_f32_16x16x32_bf16 v[30:33], v[152:155], v[200:203], v[30:33]
	v_mfma_f32_16x16x32_bf16 v[26:29], v[160:163], v[200:203], v[26:29]
	v_mfma_f32_16x16x32_bf16 v[14:17], v[152:155], v[208:211], v[14:17]
	v_mfma_f32_16x16x32_bf16 v[10:13], v[160:163], v[208:211], v[10:13]
	s_setprio 0
	s_setprio 1
	v_mfma_f32_16x16x32_bf16 v[54:57], v[164:167], v[180:183], v[54:57]
	v_mfma_f32_16x16x32_bf16 v[50:53], v[172:175], v[180:183], v[50:53]
	v_mfma_f32_16x16x32_bf16 v[38:41], v[164:167], v[188:191], v[38:41]
	v_mfma_f32_16x16x32_bf16 v[34:37], v[172:175], v[188:191], v[34:37]
	v_mfma_f32_16x16x32_bf16 v[22:25], v[164:167], v[196:199], v[22:25]
	v_mfma_f32_16x16x32_bf16 v[18:21], v[172:175], v[196:199], v[18:21]
	v_mfma_f32_16x16x32_bf16 v[6:9], v[164:167], v[204:207], v[6:9]
	v_mfma_f32_16x16x32_bf16 v[2:5], v[172:175], v[204:207], v[2:5]
	v_mfma_f32_16x16x32_bf16 v[54:57], v[168:171], v[184:187], v[54:57]
	v_mfma_f32_16x16x32_bf16 v[50:53], v[176:179], v[184:187], v[50:53]
	v_mfma_f32_16x16x32_bf16 v[38:41], v[168:171], v[192:195], v[38:41]
	v_mfma_f32_16x16x32_bf16 v[34:37], v[176:179], v[192:195], v[34:37]
	v_mfma_f32_16x16x32_bf16 v[22:25], v[168:171], v[200:203], v[22:25]
	v_mfma_f32_16x16x32_bf16 v[18:21], v[176:179], v[200:203], v[18:21]
	v_mfma_f32_16x16x32_bf16 v[6:9], v[168:171], v[208:211], v[6:9]
	v_mfma_f32_16x16x32_bf16 v[2:5], v[176:179], v[208:211], v[2:5]
	s_setprio 0
	s_barrier
	s_add_i32 s50, s50, 2
	s_add_u32 s22, s22, 0x100
	s_addc_u32 s23, s23, 0
	s_cmp_gt_u32 s50, 29
	s_cbranch_scc0 .LBB0_1174
	s_add_u32 s22, s46, 0xffffff00
	s_addc_u32 s23, s47, -1
	s_andn2_b64 vcc, exec, s[2:3]
	s_cbranch_vccnz .LBB0_1177
	v_mov_b32_e32 v2, 0
	s_mov_b32 s4, s14
	s_mov_b32 s8, s16
	s_mov_b64 s[10:11], s[20:21]
	s_mov_b32 s40, s45
	v_mov_b32_e32 v3, 0
	v_mov_b64_e32 v[4:5], 0
	v_mov_b64_e32 v[6:7], 0
	v_mov_b64_e32 v[8:9], 0
	v_mov_b64_e32 v[10:11], 0
	v_mov_b64_e32 v[12:13], 0
	v_mov_b64_e32 v[14:15], 0
	v_mov_b64_e32 v[16:17], 0
	v_mov_b64_e32 v[18:19], 0
	v_mov_b64_e32 v[20:21], 0
	v_mov_b64_e32 v[22:23], 0
	v_mov_b64_e32 v[24:25], 0
	v_mov_b64_e32 v[26:27], 0
	v_mov_b64_e32 v[28:29], 0
	v_mov_b64_e32 v[30:31], 0
	v_mov_b64_e32 v[32:33], 0
	v_mov_b64_e32 v[34:35], 0
	v_mov_b64_e32 v[36:37], 0
	v_mov_b64_e32 v[38:39], 0
	v_mov_b64_e32 v[40:41], 0
	v_mov_b64_e32 v[42:43], 0
	v_mov_b64_e32 v[44:45], 0
	v_mov_b64_e32 v[46:47], 0
	v_mov_b64_e32 v[48:49], 0
	v_mov_b64_e32 v[50:51], 0
	v_mov_b64_e32 v[52:53], 0
	v_mov_b64_e32 v[54:55], 0
	v_mov_b64_e32 v[56:57], 0
	v_mov_b64_e32 v[58:59], 0
	v_mov_b64_e32 v[60:61], 0
	v_mov_b64_e32 v[62:63], 0
	v_mov_b64_e32 v[64:65], 0
	v_mov_b64_e32 v[66:67], 0
	v_mov_b64_e32 v[68:69], 0
	v_mov_b64_e32 v[70:71], 0
	v_mov_b64_e32 v[72:73], 0
	v_mov_b64_e32 v[74:75], 0
	v_mov_b64_e32 v[76:77], 0
	v_mov_b64_e32 v[78:79], 0
	v_mov_b64_e32 v[80:81], 0
	v_mov_b64_e32 v[82:83], 0
	v_mov_b64_e32 v[84:85], 0
	v_mov_b64_e32 v[86:87], 0
	v_mov_b64_e32 v[88:89], 0
	v_mov_b64_e32 v[90:91], 0
	v_mov_b64_e32 v[92:93], 0
	v_mov_b64_e32 v[94:95], 0
	v_mov_b64_e32 v[96:97], 0
	v_mov_b64_e32 v[98:99], 0
	v_mov_b64_e32 v[100:101], 0
	v_mov_b64_e32 v[102:103], 0
	v_mov_b64_e32 v[104:105], 0
	v_mov_b64_e32 v[106:107], 0
	v_mov_b64_e32 v[108:109], 0
	v_mov_b64_e32 v[110:111], 0
	v_mov_b64_e32 v[112:113], 0
	v_mov_b64_e32 v[114:115], 0
	v_mov_b64_e32 v[116:117], 0
	v_mov_b64_e32 v[118:119], 0
	v_mov_b64_e32 v[120:121], 0
	v_mov_b64_e32 v[122:123], 0
	v_mov_b64_e32 v[124:125], 0
	v_mov_b64_e32 v[126:127], 0
	v_mov_b64_e32 v[128:129], 0
	s_andn2_b64 vcc, exec, s[0:1]
	s_cbranch_vccnz .LBB0_1178
	s_branch .LBB0_1179
